# scanner: no filler between dependent packed ops, y write after the step add (23.2 instr per step)
# baseline (speedup 1.0000x reference)
.LBB0_783:
	s_or_b64 exec, exec, s[10:11]
	v_cmp_gt_u32_e32 vcc, 64, v31
	v_cmp_eq_u32_e64 s[10:11], s4, v32
	s_or_b64 s[26:27], vcc, s[10:11]
	s_and_saveexec_b64 s[10:11], s[26:27]
	s_setprio 3
	s_or_b64 exec, exec, s[10:11]
	s_lshl_b32 s0, s94, 9
	s_and_b32 s0, s0, 0x3000
	s_mulk_i32 s0, 0x4200
	s_add_u32 s0, s24, s0
	s_addc_u32 s1, s25, 0
	s_lshl_b32 s4, s93, 8
	s_and_b32 s4, s4, 0x700
	s_add_u32 s4, s0, s4
	s_addc_u32 s5, s1, 0
	s_ashr_i32 s0, s93, 2
	s_and_b32 s30, s0, -8
	s_ashr_i32 s31, s30, 31
	s_lshl_b64 s[0:1], s[30:31], 2
	s_add_u32 s0, s4, s0
	v_cndmask_b32_e64 v28, 4, 0, vcc
	s_addc_u32 s1, s5, s1
	v_lshrrev_b32_e32 v29, 4, v30
	s_add_u32 s28, s0, 0x33f1800
	v_and_b32_e32 v32, 15, v31
	v_or_b32_e32 v95, v28, v29
	s_addc_u32 s29, s1, 0
	v_lshlrev_b32_e32 v28, 6, v95
	s_add_i32 s1, 0, 0x18000
	v_lshlrev_b32_e32 v29, 2, v32
	v_add3_u32 v102, s1, v28, v29
	v_mul_lo_u32 v28, v34, 56
	v_sub_u32_e32 v28, v144, v28
	v_cmp_lt_u32_e64 s[10:11], 15, v28
	v_lshlrev_b32_e32 v29, 3, v28
	v_lshlrev_b32_e32 v105, 4, v28
	v_add_u32_e32 v28, 0x100, v144
	v_lshlrev_b32_e32 v97, 4, v32
	v_and_b32_e32 v32, 56, v29
	v_and_b32_e32 v104, 0x1c0, v29
	v_lshrrev_b32_e32 v29, 3, v28
	v_mul_hi_u32 v29, v29, s51
	v_mul_lo_u32 v103, v34, s52
	v_mul_lo_u32 v34, v29, 56
	v_sub_u32_e32 v28, v28, v34
	v_cmp_lt_u32_e64 s[12:13], 15, v28
	v_lshlrev_b32_e32 v34, 3, v28
	v_lshlrev_b32_e32 v108, 4, v28
	v_add_u32_e32 v28, 0x200, v144
	v_mul_lo_u32 v106, v29, s52
	v_lshrrev_b32_e32 v29, 3, v28
	v_mul_hi_u32 v29, v29, s51
	v_and_b32_e32 v35, 56, v34
	v_and_b32_e32 v107, 0x1c0, v34
	v_mul_lo_u32 v34, v29, 56
	v_sub_u32_e32 v28, v28, v34
	v_cmp_lt_u32_e64 s[14:15], 15, v28
	v_lshlrev_b32_e32 v34, 3, v28
	v_lshlrev_b32_e32 v111, 4, v28
	v_add_u32_e32 v28, 0x300, v144
	v_mul_lo_u32 v109, v29, s52
	v_lshrrev_b32_e32 v29, 3, v28
	v_mul_hi_u32 v29, v29, s51
	v_and_b32_e32 v36, 56, v34
	v_and_b32_e32 v110, 0x1c0, v34
	v_mul_lo_u32 v34, v29, 56
	v_sub_u32_e32 v28, v28, v34
	v_cmp_lt_u32_e64 s[16:17], 15, v28
	v_lshlrev_b32_e32 v34, 3, v28
	v_lshlrev_b32_e32 v114, 4, v28
	v_add_u32_e32 v28, 0x400, v144
	v_mul_lo_u32 v112, v29, s52
	v_lshrrev_b32_e32 v29, 3, v28
	v_mul_hi_u32 v29, v29, s51
	v_and_b32_e32 v37, 56, v34
	v_and_b32_e32 v113, 0x1c0, v34
	v_mul_lo_u32 v34, v29, 56
	v_sub_u32_e32 v28, v28, v34
	v_cmp_lt_u32_e64 s[18:19], 15, v28
	v_lshlrev_b32_e32 v34, 3, v28
	v_lshlrev_b32_e32 v117, 4, v28
	v_add_u32_e32 v28, 0x500, v144
	v_mul_lo_u32 v115, v29, s52
	v_lshrrev_b32_e32 v29, 3, v28
	v_mul_hi_u32 v29, v29, s51
	v_and_b32_e32 v38, 56, v34
	v_and_b32_e32 v116, 0x1c0, v34
	v_mul_lo_u32 v34, v29, 56
	v_sub_u32_e32 v28, v28, v34
	v_cmp_lt_u32_e64 s[20:21], 15, v28
	v_lshlrev_b32_e32 v34, 3, v28
	v_lshlrev_b32_e32 v120, 4, v28
	v_add_u32_e32 v28, 0x600, v144
	v_mul_lo_u32 v118, v29, s52
	v_lshrrev_b32_e32 v29, 3, v28
	s_and_b32 s0, s48, 31
	v_mul_hi_u32 v29, v29, s51
	s_mul_i32 s0, s0, 0x380000
	v_and_b32_e32 v39, 56, v34
	v_and_b32_e32 v119, 0x1c0, v34
	v_mul_lo_u32 v34, v29, 56
	v_and_b32_e32 v88, 7, v31
	v_sub_u32_e32 v28, v28, v34
	v_lshlrev_b32_e32 v121, 6, v144
	v_lshlrev_b32_e32 v144, 2, v88
	s_add_u32 s0, s24, s0
	v_lshlrev_b32_e32 v34, 3, v28
	v_add_u32_e32 v125, s1, v121
	v_lshl_add_u64 v[90:91], s[28:29], 0, v[144:145]
	v_add_u32_e32 v144, v33, v30
	s_addc_u32 s1, s25, 0
	v_cmp_lt_u32_e64 s[22:23], 15, v28
	v_and_b32_e32 v40, 56, v34
	v_lshlrev_b32_e32 v124, 4, v28
	v_lshrrev_b32_e32 v28, 3, v144
	v_lshl_add_u64 v[92:93], v[144:145], 4, s[0:1]
	v_mov_b32_e32 v144, v145
	s_mov_b32 s54, 0
	v_mul_lo_u32 v122, v29, s52
	v_and_b32_e32 v123, 0x1c0, v34
	v_subrev_u32_e32 v126, 35, v28
	s_movk_i32 s31, 0xf000
	s_mov_b64 s[34:35], 0
	v_lshlrev_b32_e32 v127, 2, v32
	v_lshlrev_b32_e32 v128, 2, v35
	v_lshlrev_b32_e32 v129, 2, v36
	v_lshlrev_b32_e32 v130, 2, v37
	v_lshlrev_b32_e32 v131, 2, v38
	v_lshlrev_b32_e32 v132, 2, v39
	v_lshlrev_b32_e32 v133, 2, v40
	v_mov_b64_e32 v[32:33], v[144:145]
	v_mov_b64_e32 v[34:35], v[144:145]
	s_and_saveexec_b64 s[0:1], s[26:27]
	s_cbranch_execz .Lscan_init_done
	v_mov_b32_e32 v0, 0
	v_mov_b32_e32 v1, 0
	v_mov_b32_e32 v2, 0
	v_mov_b32_e32 v3, 0
	v_mov_b32_e32 v4, 0
	v_mov_b32_e32 v5, 0
	v_mov_b32_e32 v6, 0
	v_mov_b32_e32 v7, 0
	v_mov_b32_e32 v8, 0
	v_mov_b32_e32 v9, 0
	v_mov_b32_e32 v14, 0
	v_mov_b32_e32 v15, 0
	v_mov_b32_e32 v16, 0
	v_mov_b32_e32 v17, 0
	v_mov_b32_e32 v48, 0
	v_mov_b32_e32 v49, 0
	v_mov_b32_e32 v50, 0
	v_mov_b32_e32 v51, 0
	v_mov_b32_e32 v52, 0
	v_mov_b32_e32 v53, 0
	v_mov_b32_e32 v54, 0
	v_mov_b32_e32 v55, 0
	v_mov_b32_e32 v56, 0
	v_mov_b32_e32 v57, 0
	v_mov_b32_e32 v58, 0
	v_mov_b32_e32 v59, 0
	v_mov_b32_e32 v60, 0
	v_mov_b32_e32 v61, 0
	v_mov_b32_e32 v62, 0
	v_mov_b32_e32 v63, 0
	v_mov_b32_e32 v64, 0
	v_mov_b32_e32 v65, 0
	v_mov_b32_e32 v66, 0
	v_mov_b32_e32 v67, 0
	v_mov_b32_e32 v68, 0
	v_mov_b32_e32 v69, 0
	v_mov_b32_e32 v70, 0
	v_mov_b32_e32 v71, 0
	v_mov_b32_e32 v72, 0
	v_mov_b32_e32 v73, 0
	v_mov_b32_e32 v74, 0
	v_mov_b32_e32 v75, 0
	v_mov_b32_e32 v76, 0
	v_mov_b32_e32 v77, 0
	v_mov_b32_e32 v78, 0
	v_mov_b32_e32 v79, 0
	v_mov_b32_e32 v80, 0
	v_mov_b32_e32 v81, 0
	v_mov_b32_e32 v82, 0
	v_mov_b32_e32 v83, 0
	v_mov_b32_e32 v84, 0
	v_mov_b32_e32 v85, 0
	v_mov_b32_e32 v86, 0
	v_mov_b32_e32 v87, 0
	v_mov_b32_e32 v104, 0
	v_mov_b32_e32 v105, 0
	v_mov_b32_e32 v106, 0
	v_mov_b32_e32 v107, 0
	v_mov_b32_e32 v108, 0
	v_mov_b32_e32 v109, 0
	v_mov_b32_e32 v110, 0
	v_mov_b32_e32 v111, 0
	v_mov_b32_e32 v112, 0
	v_mov_b32_e32 v113, 0
	v_mov_b32_e32 v114, 0
	v_mov_b32_e32 v115, 0
	v_mov_b32_e32 v116, 0
	v_mov_b32_e32 v117, 0
	v_mov_b32_e32 v118, 0
	v_mov_b32_e32 v119, 0
	v_mov_b32_e32 v120, 0
	v_mov_b32_e32 v121, 0
	v_mov_b32_e32 v122, 0
	v_mov_b32_e32 v123, 0

.LBB0_787:
	s_and_saveexec_b64 s[0:1], s[8:9]
	s_xor_b64 s[36:37], exec, s[0:1]
	s_cbranch_execz .LBB0_791
	s_and_saveexec_b64 s[44:45], s[26:27]
	s_cbranch_execz .LBB0_790
	s_and_b32 s0, s54, 1
	s_mul_i32 s1, s0, 0xc000
	s_lshl_b32 s4, s30, 2
	v_add_u32_e32 v10, s1, v97
	s_add_i32 s1, s1, s4
	v_lshl_add_u32 v11, v95, 2, s1
	v_lshl_add_u32 v12, s0, 14, v102
	v_pk_fma_f32 v[4:5], v[60:61], v[64:65], v[56:57] op_sel_hi:[0,1,1]
	v_pk_fma_f32 v[6:7], v[60:61], v[66:67], v[58:59] op_sel_hi:[0,1,1]
	v_pk_mul_f32 v[80:81], v[4:5], v[80:81]
	v_pk_fma_f32 v[80:81], v[6:7], v[82:83], v[80:81]
	v_add_f32_e32 v80, v80, v81
	v_pk_mul_f32 v[76:77], v[76:77], v[2:3] op_sel_hi:[1,0]
	v_pk_mul_f32 v[78:79], v[78:79], v[2:3] op_sel_hi:[1,0]
	v_add_f32_dpp v80, v80, v80 quad_perm:[1,0,3,2] row_mask:0xf bank_mask:0xf bound_ctrl:1
	v_pk_fma_f32 v[76:77], v[4:5], v[68:69], v[76:77]
	v_pk_fma_f32 v[78:79], v[6:7], v[70:71], v[78:79]
	v_add_f32_dpp v80, v80, v80 quad_perm:[2,3,0,1] row_mask:0xf bank_mask:0xf bound_ctrl:1
	v_pk_mul_f32 v[52:53], v[52:53], v[4:5]
	v_pk_fma_f32 v[52:53], v[6:7], v[54:55], v[52:53]
	v_add_f32_dpp v80, v80, v80 row_half_mirror row_mask:0xf bank_mask:0xf bound_ctrl:1
	v_add_f32_e32 v9, v52, v53
	ds_read_b128 v[36:39], v10 offset:512
	ds_read2st64_b32 v[0:1], v11 offset0:5 offset1:11
	ds_read_b128 v[40:43], v10 offset:768
	ds_read_b128 v[28:31], v10 offset:0
	ds_read_b128 v[44:47], v10 offset:1024
	ds_read_b128 v[32:35], v10 offset:256
	v_add_f32_dpp v80, v80, v80 row_mirror row_mask:0xf bank_mask:0xf bound_ctrl:1
	v_pk_fma_f32 v[4:5], v[80:81], v[84:85], v[76:77] op_sel_hi:[0,1,1]
	v_pk_fma_f32 v[6:7], v[80:81], v[86:87], v[78:79] op_sel_hi:[0,1,1]
	v_pk_mul_f32 v[116:117], v[4:5], v[116:117]
	v_pk_fma_f32 v[116:117], v[6:7], v[118:119], v[116:117]
	v_add_f32_e32 v116, v116, v117
	v_pk_mul_f32 v[112:113], v[112:113], v[2:3] op_sel:[0,1] op_sel_hi:[1,1]
	v_pk_mul_f32 v[114:115], v[114:115], v[2:3] op_sel:[0,1] op_sel_hi:[1,1]
	v_add_f32_dpp v116, v116, v116 quad_perm:[1,0,3,2] row_mask:0xf bank_mask:0xf bound_ctrl:1
	v_pk_fma_f32 v[112:113], v[4:5], v[104:105], v[112:113]
	v_pk_fma_f32 v[114:115], v[6:7], v[106:107], v[114:115]
	v_add_f32_dpp v116, v116, v116 quad_perm:[2,3,0,1] row_mask:0xf bank_mask:0xf bound_ctrl:1
	v_pk_mul_f32 v[72:73], v[72:73], v[4:5]
	v_pk_fma_f32 v[72:73], v[6:7], v[74:75], v[72:73]
	v_add_f32_dpp v116, v116, v116 row_half_mirror row_mask:0xf bank_mask:0xf bound_ctrl:1
	v_add_f32_e32 v8, v72, v73
	ds_read_b128 v[56:59], v10 offset:2048
	ds_read_b128 v[60:63], v10 offset:2304
	ds_read_b128 v[48:51], v10 offset:1536
	ds_read_b128 v[64:67], v10 offset:2560
	ds_read_b128 v[52:55], v10 offset:1792
	ds_write2st64_b32 v12, v9, v8 offset0:0 offset1:2
	v_add_f32_dpp v116, v116, v116 row_mirror row_mask:0xf bank_mask:0xf bound_ctrl:1
	v_pk_fma_f32 v[4:5], v[116:117], v[120:121], v[112:113] op_sel_hi:[0,1,1]
	v_pk_fma_f32 v[6:7], v[116:117], v[122:123], v[114:115] op_sel_hi:[0,1,1]
	s_waitcnt lgkmcnt(6)
	v_pk_mul_f32 v[40:41], v[4:5], v[40:41]
	v_pk_fma_f32 v[40:41], v[6:7], v[42:43], v[40:41]
	v_add_f32_e32 v40, v40, v41
	v_pk_mul_f32 v[36:37], v[36:37], v[0:1] op_sel_hi:[1,0]
	v_pk_mul_f32 v[38:39], v[38:39], v[0:1] op_sel_hi:[1,0]
	v_add_f32_dpp v40, v40, v40 quad_perm:[1,0,3,2] row_mask:0xf bank_mask:0xf bound_ctrl:1
	v_pk_fma_f32 v[36:37], v[4:5], v[28:29], v[36:37]
	v_pk_fma_f32 v[38:39], v[6:7], v[30:31], v[38:39]
	v_add_f32_dpp v40, v40, v40 quad_perm:[2,3,0,1] row_mask:0xf bank_mask:0xf bound_ctrl:1
	v_pk_mul_f32 v[108:109], v[108:109], v[4:5]
	v_pk_fma_f32 v[108:109], v[6:7], v[110:111], v[108:109]
	v_add_f32_dpp v40, v40, v40 row_half_mirror row_mask:0xf bank_mask:0xf bound_ctrl:1
	v_add_f32_e32 v9, v108, v109
	ds_read_b128 v[76:79], v10 offset:3584
	ds_read2st64_b32 v[2:3], v11 offset0:17 offset1:23
	ds_read_b128 v[80:83], v10 offset:3840
	ds_read_b128 v[68:71], v10 offset:3072
	ds_read_b128 v[84:87], v10 offset:4096
	ds_read_b128 v[72:75], v10 offset:3328
	v_add_f32_dpp v40, v40, v40 row_mirror row_mask:0xf bank_mask:0xf bound_ctrl:1
	v_pk_fma_f32 v[4:5], v[40:41], v[44:45], v[36:37] op_sel_hi:[0,1,1]
	v_pk_fma_f32 v[6:7], v[40:41], v[46:47], v[38:39] op_sel_hi:[0,1,1]
	s_waitcnt lgkmcnt(7)
	v_pk_mul_f32 v[60:61], v[4:5], v[60:61]
	v_pk_fma_f32 v[60:61], v[6:7], v[62:63], v[60:61]
	v_add_f32_e32 v60, v60, v61
	v_pk_mul_f32 v[56:57], v[56:57], v[0:1] op_sel:[0,1] op_sel_hi:[1,1]
	v_pk_mul_f32 v[58:59], v[58:59], v[0:1] op_sel:[0,1] op_sel_hi:[1,1]
	v_add_f32_dpp v60, v60, v60 quad_perm:[1,0,3,2] row_mask:0xf bank_mask:0xf bound_ctrl:1
	v_pk_fma_f32 v[56:57], v[4:5], v[48:49], v[56:57]
	v_pk_fma_f32 v[58:59], v[6:7], v[50:51], v[58:59]
	v_add_f32_dpp v60, v60, v60 quad_perm:[2,3,0,1] row_mask:0xf bank_mask:0xf bound_ctrl:1
	v_pk_mul_f32 v[32:33], v[32:33], v[4:5]
	v_pk_fma_f32 v[32:33], v[6:7], v[34:35], v[32:33]
	v_add_f32_dpp v60, v60, v60 row_half_mirror row_mask:0xf bank_mask:0xf bound_ctrl:1
	v_add_f32_e32 v8, v32, v33
	ds_read_b128 v[112:115], v10 offset:5120
	ds_read_b128 v[116:119], v10 offset:5376
	ds_read_b128 v[104:107], v10 offset:4608
	ds_read_b128 v[120:123], v10 offset:5632
	ds_read_b128 v[108:111], v10 offset:4864
	ds_write2st64_b32 v12, v9, v8 offset0:4 offset1:6
	v_add_f32_dpp v60, v60, v60 row_mirror row_mask:0xf bank_mask:0xf bound_ctrl:1
	v_pk_fma_f32 v[4:5], v[60:61], v[64:65], v[56:57] op_sel_hi:[0,1,1]
	v_pk_fma_f32 v[6:7], v[60:61], v[66:67], v[58:59] op_sel_hi:[0,1,1]
	s_waitcnt lgkmcnt(6)
	v_pk_mul_f32 v[80:81], v[4:5], v[80:81]
	v_pk_fma_f32 v[80:81], v[6:7], v[82:83], v[80:81]
	v_add_f32_e32 v80, v80, v81
	v_pk_mul_f32 v[76:77], v[76:77], v[2:3] op_sel_hi:[1,0]
	v_pk_mul_f32 v[78:79], v[78:79], v[2:3] op_sel_hi:[1,0]
	v_add_f32_dpp v80, v80, v80 quad_perm:[1,0,3,2] row_mask:0xf bank_mask:0xf bound_ctrl:1
	v_pk_fma_f32 v[76:77], v[4:5], v[68:69], v[76:77]
	v_pk_fma_f32 v[78:79], v[6:7], v[70:71], v[78:79]
	v_add_f32_dpp v80, v80, v80 quad_perm:[2,3,0,1] row_mask:0xf bank_mask:0xf bound_ctrl:1
	v_pk_mul_f32 v[52:53], v[52:53], v[4:5]
	v_pk_fma_f32 v[52:53], v[6:7], v[54:55], v[52:53]
	v_add_f32_dpp v80, v80, v80 row_half_mirror row_mask:0xf bank_mask:0xf bound_ctrl:1
	v_add_f32_e32 v9, v52, v53
	ds_read_b128 v[36:39], v10 offset:6656
	ds_read2st64_b32 v[0:1], v11 offset0:29 offset1:35
	ds_read_b128 v[40:43], v10 offset:6912
	ds_read_b128 v[28:31], v10 offset:6144
	ds_read_b128 v[44:47], v10 offset:7168
	ds_read_b128 v[32:35], v10 offset:6400
	v_add_f32_dpp v80, v80, v80 row_mirror row_mask:0xf bank_mask:0xf bound_ctrl:1
	v_pk_fma_f32 v[4:5], v[80:81], v[84:85], v[76:77] op_sel_hi:[0,1,1]
	v_pk_fma_f32 v[6:7], v[80:81], v[86:87], v[78:79] op_sel_hi:[0,1,1]
	s_waitcnt lgkmcnt(7)
	v_pk_mul_f32 v[116:117], v[4:5], v[116:117]
	v_pk_fma_f32 v[116:117], v[6:7], v[118:119], v[116:117]
	v_add_f32_e32 v116, v116, v117
	v_pk_mul_f32 v[112:113], v[112:113], v[2:3] op_sel:[0,1] op_sel_hi:[1,1]
	v_pk_mul_f32 v[114:115], v[114:115], v[2:3] op_sel:[0,1] op_sel_hi:[1,1]
	v_add_f32_dpp v116, v116, v116 quad_perm:[1,0,3,2] row_mask:0xf bank_mask:0xf bound_ctrl:1
	v_pk_fma_f32 v[112:113], v[4:5], v[104:105], v[112:113]
	v_pk_fma_f32 v[114:115], v[6:7], v[106:107], v[114:115]
	v_add_f32_dpp v116, v116, v116 quad_perm:[2,3,0,1] row_mask:0xf bank_mask:0xf bound_ctrl:1
	v_pk_mul_f32 v[72:73], v[72:73], v[4:5]
	v_pk_fma_f32 v[72:73], v[6:7], v[74:75], v[72:73]
	v_add_f32_dpp v116, v116, v116 row_half_mirror row_mask:0xf bank_mask:0xf bound_ctrl:1
	v_add_f32_e32 v8, v72, v73
	ds_read_b128 v[56:59], v10 offset:8192
	ds_read_b128 v[60:63], v10 offset:8448
	ds_read_b128 v[48:51], v10 offset:7680
	ds_read_b128 v[64:67], v10 offset:8704
	ds_read_b128 v[52:55], v10 offset:7936
	ds_write2st64_b32 v12, v9, v8 offset0:8 offset1:10
	v_add_f32_dpp v116, v116, v116 row_mirror row_mask:0xf bank_mask:0xf bound_ctrl:1
	v_pk_fma_f32 v[4:5], v[116:117], v[120:121], v[112:113] op_sel_hi:[0,1,1]
	v_pk_fma_f32 v[6:7], v[116:117], v[122:123], v[114:115] op_sel_hi:[0,1,1]
	s_waitcnt lgkmcnt(6)
	v_pk_mul_f32 v[40:41], v[4:5], v[40:41]
	v_pk_fma_f32 v[40:41], v[6:7], v[42:43], v[40:41]
	v_add_f32_e32 v40, v40, v41
	v_pk_mul_f32 v[36:37], v[36:37], v[0:1] op_sel_hi:[1,0]
	v_pk_mul_f32 v[38:39], v[38:39], v[0:1] op_sel_hi:[1,0]
	v_add_f32_dpp v40, v40, v40 quad_perm:[1,0,3,2] row_mask:0xf bank_mask:0xf bound_ctrl:1
	v_pk_fma_f32 v[36:37], v[4:5], v[28:29], v[36:37]
	v_pk_fma_f32 v[38:39], v[6:7], v[30:31], v[38:39]
	v_add_f32_dpp v40, v40, v40 quad_perm:[2,3,0,1] row_mask:0xf bank_mask:0xf bound_ctrl:1
	v_pk_mul_f32 v[108:109], v[108:109], v[4:5]
	v_pk_fma_f32 v[108:109], v[6:7], v[110:111], v[108:109]
	v_add_f32_dpp v40, v40, v40 row_half_mirror row_mask:0xf bank_mask:0xf bound_ctrl:1
	v_add_f32_e32 v9, v108, v109
	ds_read_b128 v[76:79], v10 offset:9728
	ds_read2st64_b32 v[2:3], v11 offset0:41 offset1:47
	ds_read_b128 v[80:83], v10 offset:9984
	ds_read_b128 v[68:71], v10 offset:9216
	ds_read_b128 v[84:87], v10 offset:10240
	ds_read_b128 v[72:75], v10 offset:9472
	v_add_f32_dpp v40, v40, v40 row_mirror row_mask:0xf bank_mask:0xf bound_ctrl:1
	v_pk_fma_f32 v[4:5], v[40:41], v[44:45], v[36:37] op_sel_hi:[0,1,1]
	v_pk_fma_f32 v[6:7], v[40:41], v[46:47], v[38:39] op_sel_hi:[0,1,1]
	s_waitcnt lgkmcnt(7)
	v_pk_mul_f32 v[60:61], v[4:5], v[60:61]
	v_pk_fma_f32 v[60:61], v[6:7], v[62:63], v[60:61]
	v_add_f32_e32 v60, v60, v61
	v_pk_mul_f32 v[56:57], v[56:57], v[0:1] op_sel:[0,1] op_sel_hi:[1,1]
	v_pk_mul_f32 v[58:59], v[58:59], v[0:1] op_sel:[0,1] op_sel_hi:[1,1]
	v_add_f32_dpp v60, v60, v60 quad_perm:[1,0,3,2] row_mask:0xf bank_mask:0xf bound_ctrl:1
	v_pk_fma_f32 v[56:57], v[4:5], v[48:49], v[56:57]
	v_pk_fma_f32 v[58:59], v[6:7], v[50:51], v[58:59]
	v_add_f32_dpp v60, v60, v60 quad_perm:[2,3,0,1] row_mask:0xf bank_mask:0xf bound_ctrl:1
	v_pk_mul_f32 v[32:33], v[32:33], v[4:5]
	v_pk_fma_f32 v[32:33], v[6:7], v[34:35], v[32:33]
	v_add_f32_dpp v60, v60, v60 row_half_mirror row_mask:0xf bank_mask:0xf bound_ctrl:1
	v_add_f32_e32 v8, v32, v33
	ds_read_b128 v[112:115], v10 offset:11264
	ds_read_b128 v[116:119], v10 offset:11520
	ds_read_b128 v[104:107], v10 offset:10752
	ds_read_b128 v[120:123], v10 offset:11776
	ds_read_b128 v[108:111], v10 offset:11008
	ds_write2st64_b32 v12, v9, v8 offset0:12 offset1:14
	v_add_f32_dpp v60, v60, v60 row_mirror row_mask:0xf bank_mask:0xf bound_ctrl:1
	v_pk_fma_f32 v[4:5], v[60:61], v[64:65], v[56:57] op_sel_hi:[0,1,1]
	v_pk_fma_f32 v[6:7], v[60:61], v[66:67], v[58:59] op_sel_hi:[0,1,1]
	s_waitcnt lgkmcnt(6)
	v_pk_mul_f32 v[80:81], v[4:5], v[80:81]
	v_pk_fma_f32 v[80:81], v[6:7], v[82:83], v[80:81]
	v_add_f32_e32 v80, v80, v81
	v_pk_mul_f32 v[76:77], v[76:77], v[2:3] op_sel_hi:[1,0]
	v_pk_mul_f32 v[78:79], v[78:79], v[2:3] op_sel_hi:[1,0]
	v_add_f32_dpp v80, v80, v80 quad_perm:[1,0,3,2] row_mask:0xf bank_mask:0xf bound_ctrl:1
	v_pk_fma_f32 v[76:77], v[4:5], v[68:69], v[76:77]
	v_pk_fma_f32 v[78:79], v[6:7], v[70:71], v[78:79]
	v_add_f32_dpp v80, v80, v80 quad_perm:[2,3,0,1] row_mask:0xf bank_mask:0xf bound_ctrl:1
	v_pk_mul_f32 v[52:53], v[52:53], v[4:5]
	v_pk_fma_f32 v[52:53], v[6:7], v[54:55], v[52:53]
	v_add_f32_dpp v80, v80, v80 row_half_mirror row_mask:0xf bank_mask:0xf bound_ctrl:1
	v_add_f32_e32 v9, v52, v53
	ds_read_b128 v[36:39], v10 offset:12800
	ds_read2st64_b32 v[0:1], v11 offset0:53 offset1:59
	ds_read_b128 v[40:43], v10 offset:13056
	ds_read_b128 v[28:31], v10 offset:12288
	ds_read_b128 v[44:47], v10 offset:13312
	ds_read_b128 v[32:35], v10 offset:12544
	v_add_f32_dpp v80, v80, v80 row_mirror row_mask:0xf bank_mask:0xf bound_ctrl:1
	v_pk_fma_f32 v[4:5], v[80:81], v[84:85], v[76:77] op_sel_hi:[0,1,1]
	v_pk_fma_f32 v[6:7], v[80:81], v[86:87], v[78:79] op_sel_hi:[0,1,1]
	s_waitcnt lgkmcnt(7)
	v_pk_mul_f32 v[116:117], v[4:5], v[116:117]
	v_pk_fma_f32 v[116:117], v[6:7], v[118:119], v[116:117]
	v_add_f32_e32 v116, v116, v117
	v_pk_mul_f32 v[112:113], v[112:113], v[2:3] op_sel:[0,1] op_sel_hi:[1,1]
	v_pk_mul_f32 v[114:115], v[114:115], v[2:3] op_sel:[0,1] op_sel_hi:[1,1]
	v_add_f32_dpp v116, v116, v116 quad_perm:[1,0,3,2] row_mask:0xf bank_mask:0xf bound_ctrl:1
	v_pk_fma_f32 v[112:113], v[4:5], v[104:105], v[112:113]
	v_pk_fma_f32 v[114:115], v[6:7], v[106:107], v[114:115]
	v_add_f32_dpp v116, v116, v116 quad_perm:[2,3,0,1] row_mask:0xf bank_mask:0xf bound_ctrl:1
	v_pk_mul_f32 v[72:73], v[72:73], v[4:5]
	v_pk_fma_f32 v[72:73], v[6:7], v[74:75], v[72:73]
	v_add_f32_dpp v116, v116, v116 row_half_mirror row_mask:0xf bank_mask:0xf bound_ctrl:1
	v_add_f32_e32 v8, v72, v73
	ds_read_b128 v[56:59], v10 offset:14336
	ds_read_b128 v[60:63], v10 offset:14592
	ds_read_b128 v[48:51], v10 offset:13824
	ds_read_b128 v[64:67], v10 offset:14848
	ds_read_b128 v[52:55], v10 offset:14080
	ds_write2st64_b32 v12, v9, v8 offset0:16 offset1:18
	v_add_f32_dpp v116, v116, v116 row_mirror row_mask:0xf bank_mask:0xf bound_ctrl:1
	v_pk_fma_f32 v[4:5], v[116:117], v[120:121], v[112:113] op_sel_hi:[0,1,1]
	v_pk_fma_f32 v[6:7], v[116:117], v[122:123], v[114:115] op_sel_hi:[0,1,1]
	s_waitcnt lgkmcnt(6)
	v_pk_mul_f32 v[40:41], v[4:5], v[40:41]
	v_pk_fma_f32 v[40:41], v[6:7], v[42:43], v[40:41]
	v_add_f32_e32 v40, v40, v41
	v_pk_mul_f32 v[36:37], v[36:37], v[0:1] op_sel_hi:[1,0]
	v_pk_mul_f32 v[38:39], v[38:39], v[0:1] op_sel_hi:[1,0]
	v_add_f32_dpp v40, v40, v40 quad_perm:[1,0,3,2] row_mask:0xf bank_mask:0xf bound_ctrl:1
	v_pk_fma_f32 v[36:37], v[4:5], v[28:29], v[36:37]
	v_pk_fma_f32 v[38:39], v[6:7], v[30:31], v[38:39]
	v_add_f32_dpp v40, v40, v40 quad_perm:[2,3,0,1] row_mask:0xf bank_mask:0xf bound_ctrl:1
	v_pk_mul_f32 v[108:109], v[108:109], v[4:5]
	v_pk_fma_f32 v[108:109], v[6:7], v[110:111], v[108:109]
	v_add_f32_dpp v40, v40, v40 row_half_mirror row_mask:0xf bank_mask:0xf bound_ctrl:1
	v_add_f32_e32 v9, v108, v109
	ds_read_b128 v[76:79], v10 offset:15872
	ds_read2st64_b32 v[2:3], v11 offset0:65 offset1:71
	ds_read_b128 v[80:83], v10 offset:16128
	ds_read_b128 v[68:71], v10 offset:15360
	ds_read_b128 v[84:87], v10 offset:16384
	ds_read_b128 v[72:75], v10 offset:15616
	v_add_f32_dpp v40, v40, v40 row_mirror row_mask:0xf bank_mask:0xf bound_ctrl:1
	v_pk_fma_f32 v[4:5], v[40:41], v[44:45], v[36:37] op_sel_hi:[0,1,1]
	v_pk_fma_f32 v[6:7], v[40:41], v[46:47], v[38:39] op_sel_hi:[0,1,1]
	s_waitcnt lgkmcnt(7)
	v_pk_mul_f32 v[60:61], v[4:5], v[60:61]
	v_pk_fma_f32 v[60:61], v[6:7], v[62:63], v[60:61]
	v_add_f32_e32 v60, v60, v61
	v_pk_mul_f32 v[56:57], v[56:57], v[0:1] op_sel:[0,1] op_sel_hi:[1,1]
	v_pk_mul_f32 v[58:59], v[58:59], v[0:1] op_sel:[0,1] op_sel_hi:[1,1]
	v_add_f32_dpp v60, v60, v60 quad_perm:[1,0,3,2] row_mask:0xf bank_mask:0xf bound_ctrl:1
	v_pk_fma_f32 v[56:57], v[4:5], v[48:49], v[56:57]
	v_pk_fma_f32 v[58:59], v[6:7], v[50:51], v[58:59]
	v_add_f32_dpp v60, v60, v60 quad_perm:[2,3,0,1] row_mask:0xf bank_mask:0xf bound_ctrl:1
	v_pk_mul_f32 v[32:33], v[32:33], v[4:5]
	v_pk_fma_f32 v[32:33], v[6:7], v[34:35], v[32:33]
	v_add_f32_dpp v60, v60, v60 row_half_mirror row_mask:0xf bank_mask:0xf bound_ctrl:1
	v_add_f32_e32 v8, v32, v33
	ds_read_b128 v[112:115], v10 offset:17408
	ds_read_b128 v[116:119], v10 offset:17664
	ds_read_b128 v[104:107], v10 offset:16896
	ds_read_b128 v[120:123], v10 offset:17920
	ds_read_b128 v[108:111], v10 offset:17152
	ds_write2st64_b32 v12, v9, v8 offset0:20 offset1:22
	v_add_f32_dpp v60, v60, v60 row_mirror row_mask:0xf bank_mask:0xf bound_ctrl:1
	v_pk_fma_f32 v[4:5], v[60:61], v[64:65], v[56:57] op_sel_hi:[0,1,1]
	v_pk_fma_f32 v[6:7], v[60:61], v[66:67], v[58:59] op_sel_hi:[0,1,1]
	s_waitcnt lgkmcnt(6)
	v_pk_mul_f32 v[80:81], v[4:5], v[80:81]
	v_pk_fma_f32 v[80:81], v[6:7], v[82:83], v[80:81]
	v_add_f32_e32 v80, v80, v81
	v_pk_mul_f32 v[76:77], v[76:77], v[2:3] op_sel_hi:[1,0]
	v_pk_mul_f32 v[78:79], v[78:79], v[2:3] op_sel_hi:[1,0]
	v_add_f32_dpp v80, v80, v80 quad_perm:[1,0,3,2] row_mask:0xf bank_mask:0xf bound_ctrl:1
	v_pk_fma_f32 v[76:77], v[4:5], v[68:69], v[76:77]
	v_pk_fma_f32 v[78:79], v[6:7], v[70:71], v[78:79]
	v_add_f32_dpp v80, v80, v80 quad_perm:[2,3,0,1] row_mask:0xf bank_mask:0xf bound_ctrl:1
	v_pk_mul_f32 v[52:53], v[52:53], v[4:5]
	v_pk_fma_f32 v[52:53], v[6:7], v[54:55], v[52:53]
	v_add_f32_dpp v80, v80, v80 row_half_mirror row_mask:0xf bank_mask:0xf bound_ctrl:1
	v_add_f32_e32 v9, v52, v53
	ds_read_b128 v[36:39], v10 offset:18944
	ds_read2st64_b32 v[0:1], v11 offset0:77 offset1:83
	ds_read_b128 v[40:43], v10 offset:19200
	ds_read_b128 v[28:31], v10 offset:18432
	ds_read_b128 v[44:47], v10 offset:19456
	ds_read_b128 v[32:35], v10 offset:18688
	v_add_f32_dpp v80, v80, v80 row_mirror row_mask:0xf bank_mask:0xf bound_ctrl:1
	v_pk_fma_f32 v[4:5], v[80:81], v[84:85], v[76:77] op_sel_hi:[0,1,1]
	v_pk_fma_f32 v[6:7], v[80:81], v[86:87], v[78:79] op_sel_hi:[0,1,1]
	s_waitcnt lgkmcnt(7)
	v_pk_mul_f32 v[116:117], v[4:5], v[116:117]
	v_pk_fma_f32 v[116:117], v[6:7], v[118:119], v[116:117]
	v_add_f32_e32 v116, v116, v117
	v_pk_mul_f32 v[112:113], v[112:113], v[2:3] op_sel:[0,1] op_sel_hi:[1,1]
	v_pk_mul_f32 v[114:115], v[114:115], v[2:3] op_sel:[0,1] op_sel_hi:[1,1]
	v_add_f32_dpp v116, v116, v116 quad_perm:[1,0,3,2] row_mask:0xf bank_mask:0xf bound_ctrl:1
	v_pk_fma_f32 v[112:113], v[4:5], v[104:105], v[112:113]
	v_pk_fma_f32 v[114:115], v[6:7], v[106:107], v[114:115]
	v_add_f32_dpp v116, v116, v116 quad_perm:[2,3,0,1] row_mask:0xf bank_mask:0xf bound_ctrl:1
	v_pk_mul_f32 v[72:73], v[72:73], v[4:5]
	v_pk_fma_f32 v[72:73], v[6:7], v[74:75], v[72:73]
	v_add_f32_dpp v116, v116, v116 row_half_mirror row_mask:0xf bank_mask:0xf bound_ctrl:1
	v_add_f32_e32 v8, v72, v73
	ds_read_b128 v[56:59], v10 offset:20480
	ds_read_b128 v[60:63], v10 offset:20736
	ds_read_b128 v[48:51], v10 offset:19968
	ds_read_b128 v[64:67], v10 offset:20992
	ds_read_b128 v[52:55], v10 offset:20224
	ds_write2st64_b32 v12, v9, v8 offset0:24 offset1:26
	v_add_f32_dpp v116, v116, v116 row_mirror row_mask:0xf bank_mask:0xf bound_ctrl:1
	v_pk_fma_f32 v[4:5], v[116:117], v[120:121], v[112:113] op_sel_hi:[0,1,1]
	v_pk_fma_f32 v[6:7], v[116:117], v[122:123], v[114:115] op_sel_hi:[0,1,1]
	s_waitcnt lgkmcnt(6)
	v_pk_mul_f32 v[40:41], v[4:5], v[40:41]
	v_pk_fma_f32 v[40:41], v[6:7], v[42:43], v[40:41]
	v_add_f32_e32 v40, v40, v41
	v_pk_mul_f32 v[36:37], v[36:37], v[0:1] op_sel_hi:[1,0]
	v_pk_mul_f32 v[38:39], v[38:39], v[0:1] op_sel_hi:[1,0]
	v_add_f32_dpp v40, v40, v40 quad_perm:[1,0,3,2] row_mask:0xf bank_mask:0xf bound_ctrl:1
	v_pk_fma_f32 v[36:37], v[4:5], v[28:29], v[36:37]
	v_pk_fma_f32 v[38:39], v[6:7], v[30:31], v[38:39]
	v_add_f32_dpp v40, v40, v40 quad_perm:[2,3,0,1] row_mask:0xf bank_mask:0xf bound_ctrl:1
	v_pk_mul_f32 v[108:109], v[108:109], v[4:5]
	v_pk_fma_f32 v[108:109], v[6:7], v[110:111], v[108:109]
	v_add_f32_dpp v40, v40, v40 row_half_mirror row_mask:0xf bank_mask:0xf bound_ctrl:1
	v_add_f32_e32 v9, v108, v109
	ds_read_b128 v[76:79], v10 offset:22016
	ds_read2st64_b32 v[2:3], v11 offset0:89 offset1:95
	ds_read_b128 v[80:83], v10 offset:22272
	ds_read_b128 v[68:71], v10 offset:21504
	ds_read_b128 v[84:87], v10 offset:22528
	ds_read_b128 v[72:75], v10 offset:21760
	v_add_f32_dpp v40, v40, v40 row_mirror row_mask:0xf bank_mask:0xf bound_ctrl:1
	v_pk_fma_f32 v[4:5], v[40:41], v[44:45], v[36:37] op_sel_hi:[0,1,1]
	v_pk_fma_f32 v[6:7], v[40:41], v[46:47], v[38:39] op_sel_hi:[0,1,1]
	s_waitcnt lgkmcnt(7)
	v_pk_mul_f32 v[60:61], v[4:5], v[60:61]
	v_pk_fma_f32 v[60:61], v[6:7], v[62:63], v[60:61]
	v_add_f32_e32 v60, v60, v61
	v_pk_mul_f32 v[56:57], v[56:57], v[0:1] op_sel:[0,1] op_sel_hi:[1,1]
	v_pk_mul_f32 v[58:59], v[58:59], v[0:1] op_sel:[0,1] op_sel_hi:[1,1]
	v_add_f32_dpp v60, v60, v60 quad_perm:[1,0,3,2] row_mask:0xf bank_mask:0xf bound_ctrl:1
	v_pk_fma_f32 v[56:57], v[4:5], v[48:49], v[56:57]
	v_pk_fma_f32 v[58:59], v[6:7], v[50:51], v[58:59]
	v_add_f32_dpp v60, v60, v60 quad_perm:[2,3,0,1] row_mask:0xf bank_mask:0xf bound_ctrl:1
	v_pk_mul_f32 v[32:33], v[32:33], v[4:5]
	v_pk_fma_f32 v[32:33], v[6:7], v[34:35], v[32:33]
	v_add_f32_dpp v60, v60, v60 row_half_mirror row_mask:0xf bank_mask:0xf bound_ctrl:1
	v_add_f32_e32 v8, v32, v33
	ds_read_b128 v[112:115], v10 offset:23552
	ds_read_b128 v[116:119], v10 offset:23808
	ds_read_b128 v[104:107], v10 offset:23040
	ds_read_b128 v[120:123], v10 offset:24064
	ds_read_b128 v[108:111], v10 offset:23296
	ds_write2st64_b32 v12, v9, v8 offset0:28 offset1:30
	v_add_f32_dpp v60, v60, v60 row_mirror row_mask:0xf bank_mask:0xf bound_ctrl:1
	v_pk_fma_f32 v[4:5], v[60:61], v[64:65], v[56:57] op_sel_hi:[0,1,1]
	v_pk_fma_f32 v[6:7], v[60:61], v[66:67], v[58:59] op_sel_hi:[0,1,1]
	s_waitcnt lgkmcnt(6)
	v_pk_mul_f32 v[80:81], v[4:5], v[80:81]
	v_pk_fma_f32 v[80:81], v[6:7], v[82:83], v[80:81]
	v_add_f32_e32 v80, v80, v81
	v_pk_mul_f32 v[76:77], v[76:77], v[2:3] op_sel_hi:[1,0]
	v_pk_mul_f32 v[78:79], v[78:79], v[2:3] op_sel_hi:[1,0]
	v_add_f32_dpp v80, v80, v80 quad_perm:[1,0,3,2] row_mask:0xf bank_mask:0xf bound_ctrl:1
	v_pk_fma_f32 v[76:77], v[4:5], v[68:69], v[76:77]
	v_pk_fma_f32 v[78:79], v[6:7], v[70:71], v[78:79]
	v_add_f32_dpp v80, v80, v80 quad_perm:[2,3,0,1] row_mask:0xf bank_mask:0xf bound_ctrl:1
	v_pk_mul_f32 v[52:53], v[52:53], v[4:5]
	v_pk_fma_f32 v[52:53], v[6:7], v[54:55], v[52:53]
	v_add_f32_dpp v80, v80, v80 row_half_mirror row_mask:0xf bank_mask:0xf bound_ctrl:1
	v_add_f32_e32 v9, v52, v53
	ds_read_b128 v[36:39], v10 offset:25088
	ds_read2st64_b32 v[0:1], v11 offset0:101 offset1:107
	ds_read_b128 v[40:43], v10 offset:25344
	ds_read_b128 v[28:31], v10 offset:24576
	ds_read_b128 v[44:47], v10 offset:25600
	ds_read_b128 v[32:35], v10 offset:24832
	v_add_f32_dpp v80, v80, v80 row_mirror row_mask:0xf bank_mask:0xf bound_ctrl:1
	v_pk_fma_f32 v[4:5], v[80:81], v[84:85], v[76:77] op_sel_hi:[0,1,1]
	v_pk_fma_f32 v[6:7], v[80:81], v[86:87], v[78:79] op_sel_hi:[0,1,1]
	s_waitcnt lgkmcnt(7)
	v_pk_mul_f32 v[116:117], v[4:5], v[116:117]
	v_pk_fma_f32 v[116:117], v[6:7], v[118:119], v[116:117]
	v_add_f32_e32 v116, v116, v117
	v_pk_mul_f32 v[112:113], v[112:113], v[2:3] op_sel:[0,1] op_sel_hi:[1,1]
	v_pk_mul_f32 v[114:115], v[114:115], v[2:3] op_sel:[0,1] op_sel_hi:[1,1]
	v_add_f32_dpp v116, v116, v116 quad_perm:[1,0,3,2] row_mask:0xf bank_mask:0xf bound_ctrl:1
	v_pk_fma_f32 v[112:113], v[4:5], v[104:105], v[112:113]
	v_pk_fma_f32 v[114:115], v[6:7], v[106:107], v[114:115]
	v_add_f32_dpp v116, v116, v116 quad_perm:[2,3,0,1] row_mask:0xf bank_mask:0xf bound_ctrl:1
	v_pk_mul_f32 v[72:73], v[72:73], v[4:5]
	v_pk_fma_f32 v[72:73], v[6:7], v[74:75], v[72:73]
	v_add_f32_dpp v116, v116, v116 row_half_mirror row_mask:0xf bank_mask:0xf bound_ctrl:1
	v_add_f32_e32 v8, v72, v73
	ds_read_b128 v[56:59], v10 offset:26624
	ds_read_b128 v[60:63], v10 offset:26880
	ds_read_b128 v[48:51], v10 offset:26112
	ds_read_b128 v[64:67], v10 offset:27136
	ds_read_b128 v[52:55], v10 offset:26368
	ds_write2st64_b32 v12, v9, v8 offset0:32 offset1:34
	v_add_f32_dpp v116, v116, v116 row_mirror row_mask:0xf bank_mask:0xf bound_ctrl:1
	v_pk_fma_f32 v[4:5], v[116:117], v[120:121], v[112:113] op_sel_hi:[0,1,1]
	v_pk_fma_f32 v[6:7], v[116:117], v[122:123], v[114:115] op_sel_hi:[0,1,1]
	s_waitcnt lgkmcnt(6)
	v_pk_mul_f32 v[40:41], v[4:5], v[40:41]
	v_pk_fma_f32 v[40:41], v[6:7], v[42:43], v[40:41]
	v_add_f32_e32 v40, v40, v41
	v_pk_mul_f32 v[36:37], v[36:37], v[0:1] op_sel_hi:[1,0]
	v_pk_mul_f32 v[38:39], v[38:39], v[0:1] op_sel_hi:[1,0]
	v_add_f32_dpp v40, v40, v40 quad_perm:[1,0,3,2] row_mask:0xf bank_mask:0xf bound_ctrl:1
	v_pk_fma_f32 v[36:37], v[4:5], v[28:29], v[36:37]
	v_pk_fma_f32 v[38:39], v[6:7], v[30:31], v[38:39]
	v_add_f32_dpp v40, v40, v40 quad_perm:[2,3,0,1] row_mask:0xf bank_mask:0xf bound_ctrl:1
	v_pk_mul_f32 v[108:109], v[108:109], v[4:5]
	v_pk_fma_f32 v[108:109], v[6:7], v[110:111], v[108:109]
	v_add_f32_dpp v40, v40, v40 row_half_mirror row_mask:0xf bank_mask:0xf bound_ctrl:1
	v_add_f32_e32 v9, v108, v109
	ds_read_b128 v[76:79], v10 offset:28160
	ds_read2st64_b32 v[2:3], v11 offset0:113 offset1:119
	ds_read_b128 v[80:83], v10 offset:28416
	ds_read_b128 v[68:71], v10 offset:27648
	ds_read_b128 v[84:87], v10 offset:28672
	ds_read_b128 v[72:75], v10 offset:27904
	v_add_f32_dpp v40, v40, v40 row_mirror row_mask:0xf bank_mask:0xf bound_ctrl:1
	v_pk_fma_f32 v[4:5], v[40:41], v[44:45], v[36:37] op_sel_hi:[0,1,1]
	v_pk_fma_f32 v[6:7], v[40:41], v[46:47], v[38:39] op_sel_hi:[0,1,1]
	s_waitcnt lgkmcnt(7)
	v_pk_mul_f32 v[60:61], v[4:5], v[60:61]
	v_pk_fma_f32 v[60:61], v[6:7], v[62:63], v[60:61]
	v_add_f32_e32 v60, v60, v61
	v_pk_mul_f32 v[56:57], v[56:57], v[0:1] op_sel:[0,1] op_sel_hi:[1,1]
	v_pk_mul_f32 v[58:59], v[58:59], v[0:1] op_sel:[0,1] op_sel_hi:[1,1]
	v_add_f32_dpp v60, v60, v60 quad_perm:[1,0,3,2] row_mask:0xf bank_mask:0xf bound_ctrl:1
	v_pk_fma_f32 v[56:57], v[4:5], v[48:49], v[56:57]
	v_pk_fma_f32 v[58:59], v[6:7], v[50:51], v[58:59]
	v_add_f32_dpp v60, v60, v60 quad_perm:[2,3,0,1] row_mask:0xf bank_mask:0xf bound_ctrl:1
	v_pk_mul_f32 v[32:33], v[32:33], v[4:5]
	v_pk_fma_f32 v[32:33], v[6:7], v[34:35], v[32:33]
	v_add_f32_dpp v60, v60, v60 row_half_mirror row_mask:0xf bank_mask:0xf bound_ctrl:1
	v_add_f32_e32 v8, v32, v33
	ds_read_b128 v[112:115], v10 offset:29696
	ds_read_b128 v[116:119], v10 offset:29952
	ds_read_b128 v[104:107], v10 offset:29184
	ds_read_b128 v[120:123], v10 offset:30208
	ds_read_b128 v[108:111], v10 offset:29440
	ds_write2st64_b32 v12, v9, v8 offset0:36 offset1:38
	v_add_f32_dpp v60, v60, v60 row_mirror row_mask:0xf bank_mask:0xf bound_ctrl:1
	v_pk_fma_f32 v[4:5], v[60:61], v[64:65], v[56:57] op_sel_hi:[0,1,1]
	v_pk_fma_f32 v[6:7], v[60:61], v[66:67], v[58:59] op_sel_hi:[0,1,1]
	s_waitcnt lgkmcnt(6)
	v_pk_mul_f32 v[80:81], v[4:5], v[80:81]
	v_pk_fma_f32 v[80:81], v[6:7], v[82:83], v[80:81]
	v_add_f32_e32 v80, v80, v81
	v_pk_mul_f32 v[76:77], v[76:77], v[2:3] op_sel_hi:[1,0]
	v_pk_mul_f32 v[78:79], v[78:79], v[2:3] op_sel_hi:[1,0]
	v_add_f32_dpp v80, v80, v80 quad_perm:[1,0,3,2] row_mask:0xf bank_mask:0xf bound_ctrl:1
	v_pk_fma_f32 v[76:77], v[4:5], v[68:69], v[76:77]
	v_pk_fma_f32 v[78:79], v[6:7], v[70:71], v[78:79]
	v_add_f32_dpp v80, v80, v80 quad_perm:[2,3,0,1] row_mask:0xf bank_mask:0xf bound_ctrl:1
	v_pk_mul_f32 v[52:53], v[52:53], v[4:5]
	v_pk_fma_f32 v[52:53], v[6:7], v[54:55], v[52:53]
	v_add_f32_dpp v80, v80, v80 row_half_mirror row_mask:0xf bank_mask:0xf bound_ctrl:1
	v_add_f32_e32 v9, v52, v53
	ds_read_b128 v[36:39], v10 offset:31232
	ds_read2st64_b32 v[0:1], v11 offset0:125 offset1:131
	ds_read_b128 v[40:43], v10 offset:31488
	ds_read_b128 v[28:31], v10 offset:30720
	ds_read_b128 v[44:47], v10 offset:31744
	ds_read_b128 v[32:35], v10 offset:30976
	v_add_f32_dpp v80, v80, v80 row_mirror row_mask:0xf bank_mask:0xf bound_ctrl:1
	v_pk_fma_f32 v[4:5], v[80:81], v[84:85], v[76:77] op_sel_hi:[0,1,1]
	v_pk_fma_f32 v[6:7], v[80:81], v[86:87], v[78:79] op_sel_hi:[0,1,1]
	s_waitcnt lgkmcnt(7)
	v_pk_mul_f32 v[116:117], v[4:5], v[116:117]
	v_pk_fma_f32 v[116:117], v[6:7], v[118:119], v[116:117]
	v_add_f32_e32 v116, v116, v117
	v_pk_mul_f32 v[112:113], v[112:113], v[2:3] op_sel:[0,1] op_sel_hi:[1,1]
	v_pk_mul_f32 v[114:115], v[114:115], v[2:3] op_sel:[0,1] op_sel_hi:[1,1]
	v_add_f32_dpp v116, v116, v116 quad_perm:[1,0,3,2] row_mask:0xf bank_mask:0xf bound_ctrl:1
	v_pk_fma_f32 v[112:113], v[4:5], v[104:105], v[112:113]
	v_pk_fma_f32 v[114:115], v[6:7], v[106:107], v[114:115]
	v_add_f32_dpp v116, v116, v116 quad_perm:[2,3,0,1] row_mask:0xf bank_mask:0xf bound_ctrl:1
	v_pk_mul_f32 v[72:73], v[72:73], v[4:5]
	v_pk_fma_f32 v[72:73], v[6:7], v[74:75], v[72:73]
	v_add_f32_dpp v116, v116, v116 row_half_mirror row_mask:0xf bank_mask:0xf bound_ctrl:1
	v_add_f32_e32 v8, v72, v73
	ds_read_b128 v[56:59], v10 offset:32768
	ds_read_b128 v[60:63], v10 offset:33024
	ds_read_b128 v[48:51], v10 offset:32256
	ds_read_b128 v[64:67], v10 offset:33280
	ds_read_b128 v[52:55], v10 offset:32512
	ds_write2st64_b32 v12, v9, v8 offset0:40 offset1:42
	v_add_f32_dpp v116, v116, v116 row_mirror row_mask:0xf bank_mask:0xf bound_ctrl:1
	v_pk_fma_f32 v[4:5], v[116:117], v[120:121], v[112:113] op_sel_hi:[0,1,1]
	v_pk_fma_f32 v[6:7], v[116:117], v[122:123], v[114:115] op_sel_hi:[0,1,1]
	s_waitcnt lgkmcnt(6)
	v_pk_mul_f32 v[40:41], v[4:5], v[40:41]
	v_pk_fma_f32 v[40:41], v[6:7], v[42:43], v[40:41]
	v_add_f32_e32 v40, v40, v41
	v_pk_mul_f32 v[36:37], v[36:37], v[0:1] op_sel_hi:[1,0]
	v_pk_mul_f32 v[38:39], v[38:39], v[0:1] op_sel_hi:[1,0]
	v_add_f32_dpp v40, v40, v40 quad_perm:[1,0,3,2] row_mask:0xf bank_mask:0xf bound_ctrl:1
	v_pk_fma_f32 v[36:37], v[4:5], v[28:29], v[36:37]
	v_pk_fma_f32 v[38:39], v[6:7], v[30:31], v[38:39]
	v_add_f32_dpp v40, v40, v40 quad_perm:[2,3,0,1] row_mask:0xf bank_mask:0xf bound_ctrl:1
	v_pk_mul_f32 v[108:109], v[108:109], v[4:5]
	v_pk_fma_f32 v[108:109], v[6:7], v[110:111], v[108:109]
	v_add_f32_dpp v40, v40, v40 row_half_mirror row_mask:0xf bank_mask:0xf bound_ctrl:1
	v_add_f32_e32 v9, v108, v109
	ds_read_b128 v[76:79], v10 offset:34304
	ds_read2st64_b32 v[2:3], v11 offset0:137 offset1:143
	ds_read_b128 v[80:83], v10 offset:34560
	ds_read_b128 v[68:71], v10 offset:33792
	ds_read_b128 v[84:87], v10 offset:34816
	ds_read_b128 v[72:75], v10 offset:34048
	v_add_f32_dpp v40, v40, v40 row_mirror row_mask:0xf bank_mask:0xf bound_ctrl:1
	v_pk_fma_f32 v[4:5], v[40:41], v[44:45], v[36:37] op_sel_hi:[0,1,1]
	v_pk_fma_f32 v[6:7], v[40:41], v[46:47], v[38:39] op_sel_hi:[0,1,1]
	s_waitcnt lgkmcnt(7)
	v_pk_mul_f32 v[60:61], v[4:5], v[60:61]
	v_pk_fma_f32 v[60:61], v[6:7], v[62:63], v[60:61]
	v_add_f32_e32 v60, v60, v61
	v_pk_mul_f32 v[56:57], v[56:57], v[0:1] op_sel:[0,1] op_sel_hi:[1,1]
	v_pk_mul_f32 v[58:59], v[58:59], v[0:1] op_sel:[0,1] op_sel_hi:[1,1]
	v_add_f32_dpp v60, v60, v60 quad_perm:[1,0,3,2] row_mask:0xf bank_mask:0xf bound_ctrl:1
	v_pk_fma_f32 v[56:57], v[4:5], v[48:49], v[56:57]
	v_pk_fma_f32 v[58:59], v[6:7], v[50:51], v[58:59]
	v_add_f32_dpp v60, v60, v60 quad_perm:[2,3,0,1] row_mask:0xf bank_mask:0xf bound_ctrl:1
	v_pk_mul_f32 v[32:33], v[32:33], v[4:5]
	v_pk_fma_f32 v[32:33], v[6:7], v[34:35], v[32:33]
	v_add_f32_dpp v60, v60, v60 row_half_mirror row_mask:0xf bank_mask:0xf bound_ctrl:1
	v_add_f32_e32 v8, v32, v33
	ds_read_b128 v[112:115], v10 offset:35840
	ds_read_b128 v[116:119], v10 offset:36096
	ds_read_b128 v[104:107], v10 offset:35328
	ds_read_b128 v[120:123], v10 offset:36352
	ds_read_b128 v[108:111], v10 offset:35584
	ds_write2st64_b32 v12, v9, v8 offset0:44 offset1:46
	v_add_f32_dpp v60, v60, v60 row_mirror row_mask:0xf bank_mask:0xf bound_ctrl:1
	v_pk_fma_f32 v[4:5], v[60:61], v[64:65], v[56:57] op_sel_hi:[0,1,1]
	v_pk_fma_f32 v[6:7], v[60:61], v[66:67], v[58:59] op_sel_hi:[0,1,1]
	s_waitcnt lgkmcnt(6)
	v_pk_mul_f32 v[80:81], v[4:5], v[80:81]
	v_pk_fma_f32 v[80:81], v[6:7], v[82:83], v[80:81]
	v_add_f32_e32 v80, v80, v81
	v_pk_mul_f32 v[76:77], v[76:77], v[2:3] op_sel_hi:[1,0]
	v_pk_mul_f32 v[78:79], v[78:79], v[2:3] op_sel_hi:[1,0]
	v_add_f32_dpp v80, v80, v80 quad_perm:[1,0,3,2] row_mask:0xf bank_mask:0xf bound_ctrl:1
	v_pk_fma_f32 v[76:77], v[4:5], v[68:69], v[76:77]
	v_pk_fma_f32 v[78:79], v[6:7], v[70:71], v[78:79]
	v_add_f32_dpp v80, v80, v80 quad_perm:[2,3,0,1] row_mask:0xf bank_mask:0xf bound_ctrl:1
	v_pk_mul_f32 v[52:53], v[52:53], v[4:5]
	v_pk_fma_f32 v[52:53], v[6:7], v[54:55], v[52:53]
	v_add_f32_dpp v80, v80, v80 row_half_mirror row_mask:0xf bank_mask:0xf bound_ctrl:1
	v_add_f32_e32 v9, v52, v53
	ds_read_b128 v[36:39], v10 offset:37376
	ds_read2st64_b32 v[0:1], v11 offset0:149 offset1:155
	ds_read_b128 v[40:43], v10 offset:37632
	ds_read_b128 v[28:31], v10 offset:36864
	ds_read_b128 v[44:47], v10 offset:37888
	ds_read_b128 v[32:35], v10 offset:37120
	v_add_f32_dpp v80, v80, v80 row_mirror row_mask:0xf bank_mask:0xf bound_ctrl:1
	v_pk_fma_f32 v[4:5], v[80:81], v[84:85], v[76:77] op_sel_hi:[0,1,1]
	v_pk_fma_f32 v[6:7], v[80:81], v[86:87], v[78:79] op_sel_hi:[0,1,1]
	s_waitcnt lgkmcnt(7)
	v_pk_mul_f32 v[116:117], v[4:5], v[116:117]
	v_pk_fma_f32 v[116:117], v[6:7], v[118:119], v[116:117]
	v_add_f32_e32 v116, v116, v117
	v_pk_mul_f32 v[112:113], v[112:113], v[2:3] op_sel:[0,1] op_sel_hi:[1,1]
	v_pk_mul_f32 v[114:115], v[114:115], v[2:3] op_sel:[0,1] op_sel_hi:[1,1]
	v_add_f32_dpp v116, v116, v116 quad_perm:[1,0,3,2] row_mask:0xf bank_mask:0xf bound_ctrl:1
	v_pk_fma_f32 v[112:113], v[4:5], v[104:105], v[112:113]
	v_pk_fma_f32 v[114:115], v[6:7], v[106:107], v[114:115]
	v_add_f32_dpp v116, v116, v116 quad_perm:[2,3,0,1] row_mask:0xf bank_mask:0xf bound_ctrl:1
	v_pk_mul_f32 v[72:73], v[72:73], v[4:5]
	v_pk_fma_f32 v[72:73], v[6:7], v[74:75], v[72:73]
	v_add_f32_dpp v116, v116, v116 row_half_mirror row_mask:0xf bank_mask:0xf bound_ctrl:1
	v_add_f32_e32 v8, v72, v73
	ds_read_b128 v[56:59], v10 offset:38912
	ds_read_b128 v[60:63], v10 offset:39168
	ds_read_b128 v[48:51], v10 offset:38400
	ds_read_b128 v[64:67], v10 offset:39424
	ds_read_b128 v[52:55], v10 offset:38656
	ds_write2st64_b32 v12, v9, v8 offset0:48 offset1:50
	v_add_f32_dpp v116, v116, v116 row_mirror row_mask:0xf bank_mask:0xf bound_ctrl:1
	v_pk_fma_f32 v[4:5], v[116:117], v[120:121], v[112:113] op_sel_hi:[0,1,1]
	v_pk_fma_f32 v[6:7], v[116:117], v[122:123], v[114:115] op_sel_hi:[0,1,1]
	s_waitcnt lgkmcnt(6)
	v_pk_mul_f32 v[40:41], v[4:5], v[40:41]
	v_pk_fma_f32 v[40:41], v[6:7], v[42:43], v[40:41]
	v_add_f32_e32 v40, v40, v41
	v_pk_mul_f32 v[36:37], v[36:37], v[0:1] op_sel_hi:[1,0]
	v_pk_mul_f32 v[38:39], v[38:39], v[0:1] op_sel_hi:[1,0]
	v_add_f32_dpp v40, v40, v40 quad_perm:[1,0,3,2] row_mask:0xf bank_mask:0xf bound_ctrl:1
	v_pk_fma_f32 v[36:37], v[4:5], v[28:29], v[36:37]
	v_pk_fma_f32 v[38:39], v[6:7], v[30:31], v[38:39]
	v_add_f32_dpp v40, v40, v40 quad_perm:[2,3,0,1] row_mask:0xf bank_mask:0xf bound_ctrl:1
	v_pk_mul_f32 v[108:109], v[108:109], v[4:5]
	v_pk_fma_f32 v[108:109], v[6:7], v[110:111], v[108:109]
	v_add_f32_dpp v40, v40, v40 row_half_mirror row_mask:0xf bank_mask:0xf bound_ctrl:1
	v_add_f32_e32 v9, v108, v109
	ds_read_b128 v[76:79], v10 offset:40448
	ds_read2st64_b32 v[2:3], v11 offset0:161 offset1:167
	ds_read_b128 v[80:83], v10 offset:40704
	ds_read_b128 v[68:71], v10 offset:39936
	ds_read_b128 v[84:87], v10 offset:40960
	ds_read_b128 v[72:75], v10 offset:40192
	v_add_f32_dpp v40, v40, v40 row_mirror row_mask:0xf bank_mask:0xf bound_ctrl:1
	v_pk_fma_f32 v[4:5], v[40:41], v[44:45], v[36:37] op_sel_hi:[0,1,1]
	v_pk_fma_f32 v[6:7], v[40:41], v[46:47], v[38:39] op_sel_hi:[0,1,1]
	s_waitcnt lgkmcnt(7)
	v_pk_mul_f32 v[60:61], v[4:5], v[60:61]
	v_pk_fma_f32 v[60:61], v[6:7], v[62:63], v[60:61]
	v_add_f32_e32 v60, v60, v61
	v_pk_mul_f32 v[56:57], v[56:57], v[0:1] op_sel:[0,1] op_sel_hi:[1,1]
	v_pk_mul_f32 v[58:59], v[58:59], v[0:1] op_sel:[0,1] op_sel_hi:[1,1]
	v_add_f32_dpp v60, v60, v60 quad_perm:[1,0,3,2] row_mask:0xf bank_mask:0xf bound_ctrl:1
	v_pk_fma_f32 v[56:57], v[4:5], v[48:49], v[56:57]
	v_pk_fma_f32 v[58:59], v[6:7], v[50:51], v[58:59]
	v_add_f32_dpp v60, v60, v60 quad_perm:[2,3,0,1] row_mask:0xf bank_mask:0xf bound_ctrl:1
	v_pk_mul_f32 v[32:33], v[32:33], v[4:5]
	v_pk_fma_f32 v[32:33], v[6:7], v[34:35], v[32:33]
	v_add_f32_dpp v60, v60, v60 row_half_mirror row_mask:0xf bank_mask:0xf bound_ctrl:1
	v_add_f32_e32 v8, v32, v33
	ds_read_b128 v[112:115], v10 offset:41984
	ds_read_b128 v[116:119], v10 offset:42240
	ds_read_b128 v[104:107], v10 offset:41472
	ds_read_b128 v[120:123], v10 offset:42496
	ds_read_b128 v[108:111], v10 offset:41728
	ds_write2st64_b32 v12, v9, v8 offset0:52 offset1:54
	v_add_f32_dpp v60, v60, v60 row_mirror row_mask:0xf bank_mask:0xf bound_ctrl:1
	v_pk_fma_f32 v[4:5], v[60:61], v[64:65], v[56:57] op_sel_hi:[0,1,1]
	v_pk_fma_f32 v[6:7], v[60:61], v[66:67], v[58:59] op_sel_hi:[0,1,1]
	s_waitcnt lgkmcnt(6)
	v_pk_mul_f32 v[80:81], v[4:5], v[80:81]
	v_pk_fma_f32 v[80:81], v[6:7], v[82:83], v[80:81]
	v_add_f32_e32 v80, v80, v81
	v_pk_mul_f32 v[76:77], v[76:77], v[2:3] op_sel_hi:[1,0]
	v_pk_mul_f32 v[78:79], v[78:79], v[2:3] op_sel_hi:[1,0]
	v_add_f32_dpp v80, v80, v80 quad_perm:[1,0,3,2] row_mask:0xf bank_mask:0xf bound_ctrl:1
	v_pk_fma_f32 v[76:77], v[4:5], v[68:69], v[76:77]
	v_pk_fma_f32 v[78:79], v[6:7], v[70:71], v[78:79]
	v_add_f32_dpp v80, v80, v80 quad_perm:[2,3,0,1] row_mask:0xf bank_mask:0xf bound_ctrl:1
	v_pk_mul_f32 v[52:53], v[52:53], v[4:5]
	v_pk_fma_f32 v[52:53], v[6:7], v[54:55], v[52:53]
	v_add_f32_dpp v80, v80, v80 row_half_mirror row_mask:0xf bank_mask:0xf bound_ctrl:1
	v_add_f32_e32 v9, v52, v53
	ds_read_b128 v[36:39], v10 offset:43520
	ds_read2st64_b32 v[0:1], v11 offset0:173 offset1:179
	ds_read_b128 v[40:43], v10 offset:43776
	ds_read_b128 v[28:31], v10 offset:43008
	ds_read_b128 v[44:47], v10 offset:44032
	ds_read_b128 v[32:35], v10 offset:43264
	v_add_f32_dpp v80, v80, v80 row_mirror row_mask:0xf bank_mask:0xf bound_ctrl:1
	v_pk_fma_f32 v[4:5], v[80:81], v[84:85], v[76:77] op_sel_hi:[0,1,1]
	v_pk_fma_f32 v[6:7], v[80:81], v[86:87], v[78:79] op_sel_hi:[0,1,1]
	s_waitcnt lgkmcnt(7)
	v_pk_mul_f32 v[116:117], v[4:5], v[116:117]
	v_pk_fma_f32 v[116:117], v[6:7], v[118:119], v[116:117]
	v_add_f32_e32 v116, v116, v117
	v_pk_mul_f32 v[112:113], v[112:113], v[2:3] op_sel:[0,1] op_sel_hi:[1,1]
	v_pk_mul_f32 v[114:115], v[114:115], v[2:3] op_sel:[0,1] op_sel_hi:[1,1]
	v_add_f32_dpp v116, v116, v116 quad_perm:[1,0,3,2] row_mask:0xf bank_mask:0xf bound_ctrl:1
	v_pk_fma_f32 v[112:113], v[4:5], v[104:105], v[112:113]
	v_pk_fma_f32 v[114:115], v[6:7], v[106:107], v[114:115]
	v_add_f32_dpp v116, v116, v116 quad_perm:[2,3,0,1] row_mask:0xf bank_mask:0xf bound_ctrl:1
	v_pk_mul_f32 v[72:73], v[72:73], v[4:5]
	v_pk_fma_f32 v[72:73], v[6:7], v[74:75], v[72:73]
	v_add_f32_dpp v116, v116, v116 row_half_mirror row_mask:0xf bank_mask:0xf bound_ctrl:1
	v_add_f32_e32 v8, v72, v73
	ds_read_b128 v[56:59], v10 offset:45056
	ds_read_b128 v[60:63], v10 offset:45312
	ds_read_b128 v[48:51], v10 offset:44544
	ds_read_b128 v[64:67], v10 offset:45568
	ds_read_b128 v[52:55], v10 offset:44800
	ds_write2st64_b32 v12, v9, v8 offset0:56 offset1:58
	v_add_f32_dpp v116, v116, v116 row_mirror row_mask:0xf bank_mask:0xf bound_ctrl:1
	v_pk_fma_f32 v[4:5], v[116:117], v[120:121], v[112:113] op_sel_hi:[0,1,1]
	v_pk_fma_f32 v[6:7], v[116:117], v[122:123], v[114:115] op_sel_hi:[0,1,1]
	s_waitcnt lgkmcnt(6)
	v_pk_mul_f32 v[40:41], v[4:5], v[40:41]
	v_pk_fma_f32 v[40:41], v[6:7], v[42:43], v[40:41]
	v_add_f32_e32 v40, v40, v41
	v_pk_mul_f32 v[36:37], v[36:37], v[0:1] op_sel_hi:[1,0]
	v_pk_mul_f32 v[38:39], v[38:39], v[0:1] op_sel_hi:[1,0]
	v_add_f32_dpp v40, v40, v40 quad_perm:[1,0,3,2] row_mask:0xf bank_mask:0xf bound_ctrl:1
	v_pk_fma_f32 v[36:37], v[4:5], v[28:29], v[36:37]
	v_pk_fma_f32 v[38:39], v[6:7], v[30:31], v[38:39]
	v_add_f32_dpp v40, v40, v40 quad_perm:[2,3,0,1] row_mask:0xf bank_mask:0xf bound_ctrl:1
	v_pk_mul_f32 v[108:109], v[108:109], v[4:5]
	v_pk_fma_f32 v[108:109], v[6:7], v[110:111], v[108:109]
	v_add_f32_dpp v40, v40, v40 row_half_mirror row_mask:0xf bank_mask:0xf bound_ctrl:1
	v_add_f32_e32 v9, v108, v109
	ds_read_b128 v[76:79], v10 offset:46592
	ds_read2st64_b32 v[2:3], v11 offset0:185 offset1:191
	ds_read_b128 v[80:83], v10 offset:46848
	ds_read_b128 v[68:71], v10 offset:46080
	ds_read_b128 v[84:87], v10 offset:47104
	ds_read_b128 v[72:75], v10 offset:46336
	v_add_f32_dpp v40, v40, v40 row_mirror row_mask:0xf bank_mask:0xf bound_ctrl:1
	v_pk_fma_f32 v[4:5], v[40:41], v[44:45], v[36:37] op_sel_hi:[0,1,1]
	v_pk_fma_f32 v[6:7], v[40:41], v[46:47], v[38:39] op_sel_hi:[0,1,1]
	s_waitcnt lgkmcnt(7)
	v_pk_mul_f32 v[60:61], v[4:5], v[60:61]
	v_pk_fma_f32 v[60:61], v[6:7], v[62:63], v[60:61]
	v_add_f32_e32 v60, v60, v61
	v_pk_mul_f32 v[56:57], v[56:57], v[0:1] op_sel:[0,1] op_sel_hi:[1,1]
	v_pk_mul_f32 v[58:59], v[58:59], v[0:1] op_sel:[0,1] op_sel_hi:[1,1]
	v_add_f32_dpp v60, v60, v60 quad_perm:[1,0,3,2] row_mask:0xf bank_mask:0xf bound_ctrl:1
	v_pk_fma_f32 v[56:57], v[4:5], v[48:49], v[56:57]
	v_pk_fma_f32 v[58:59], v[6:7], v[50:51], v[58:59]
	v_add_f32_dpp v60, v60, v60 quad_perm:[2,3,0,1] row_mask:0xf bank_mask:0xf bound_ctrl:1
	v_pk_mul_f32 v[32:33], v[32:33], v[4:5]
	v_pk_fma_f32 v[32:33], v[6:7], v[34:35], v[32:33]
	v_add_f32_dpp v60, v60, v60 row_half_mirror row_mask:0xf bank_mask:0xf bound_ctrl:1
	v_add_f32_e32 v8, v32, v33
	ds_read_b128 v[112:115], v10 offset:48128
	ds_read_b128 v[116:119], v10 offset:48384
	ds_read_b128 v[104:107], v10 offset:47616
	ds_read_b128 v[120:123], v10 offset:48640
	ds_read_b128 v[108:111], v10 offset:47872
	ds_write2st64_b32 v12, v9, v8 offset0:60 offset1:62
	v_add_f32_dpp v60, v60, v60 row_mirror row_mask:0xf bank_mask:0xf bound_ctrl:1

.LBB0_826:
	s_and_saveexec_b64 s[8:9], s[26:27]
	s_cbranch_execz .Lscan_epi_done
	v_mov_b32_e32 v12, v102
	v_pk_fma_f32 v[4:5], v[60:61], v[64:65], v[56:57] op_sel_hi:[0,1,1]
	v_pk_fma_f32 v[6:7], v[60:61], v[66:67], v[58:59] op_sel_hi:[0,1,1]
	v_pk_mul_f32 v[80:81], v[4:5], v[80:81]
	v_pk_fma_f32 v[80:81], v[6:7], v[82:83], v[80:81]
	v_add_f32_e32 v80, v80, v81
	v_pk_mul_f32 v[76:77], v[76:77], v[2:3] op_sel_hi:[1,0]
	v_pk_mul_f32 v[78:79], v[78:79], v[2:3] op_sel_hi:[1,0]
	v_add_f32_dpp v80, v80, v80 quad_perm:[1,0,3,2] row_mask:0xf bank_mask:0xf bound_ctrl:1
	v_pk_fma_f32 v[76:77], v[4:5], v[68:69], v[76:77]
	v_pk_fma_f32 v[78:79], v[6:7], v[70:71], v[78:79]
	v_add_f32_dpp v80, v80, v80 quad_perm:[2,3,0,1] row_mask:0xf bank_mask:0xf bound_ctrl:1
	v_pk_mul_f32 v[52:53], v[52:53], v[4:5]
	v_pk_fma_f32 v[52:53], v[6:7], v[54:55], v[52:53]
	v_add_f32_dpp v80, v80, v80 row_half_mirror row_mask:0xf bank_mask:0xf bound_ctrl:1
	v_add_f32_e32 v9, v52, v53
	s_nop 0
	v_add_f32_dpp v80, v80, v80 row_mirror row_mask:0xf bank_mask:0xf bound_ctrl:1
	v_pk_fma_f32 v[4:5], v[80:81], v[84:85], v[76:77] op_sel_hi:[0,1,1]
	v_pk_fma_f32 v[6:7], v[80:81], v[86:87], v[78:79] op_sel_hi:[0,1,1]
	v_pk_mul_f32 v[116:117], v[4:5], v[116:117]
	v_pk_fma_f32 v[116:117], v[6:7], v[118:119], v[116:117]
	v_add_f32_e32 v116, v116, v117
	v_pk_mul_f32 v[112:113], v[112:113], v[2:3] op_sel:[0,1] op_sel_hi:[1,1]
	v_pk_mul_f32 v[114:115], v[114:115], v[2:3] op_sel:[0,1] op_sel_hi:[1,1]
	v_add_f32_dpp v116, v116, v116 quad_perm:[1,0,3,2] row_mask:0xf bank_mask:0xf bound_ctrl:1
	v_pk_fma_f32 v[112:113], v[4:5], v[104:105], v[112:113]
	v_pk_fma_f32 v[114:115], v[6:7], v[106:107], v[114:115]
	v_add_f32_dpp v116, v116, v116 quad_perm:[2,3,0,1] row_mask:0xf bank_mask:0xf bound_ctrl:1
	v_pk_mul_f32 v[72:73], v[72:73], v[4:5]
	v_pk_fma_f32 v[72:73], v[6:7], v[74:75], v[72:73]
	v_add_f32_dpp v116, v116, v116 row_half_mirror row_mask:0xf bank_mask:0xf bound_ctrl:1
	v_add_f32_e32 v8, v72, v73
	ds_write2st64_b32 v12, v9, v8 offset0:0 offset1:2
	v_add_f32_dpp v116, v116, v116 row_mirror row_mask:0xf bank_mask:0xf bound_ctrl:1
	v_pk_fma_f32 v[4:5], v[116:117], v[120:121], v[112:113] op_sel_hi:[0,1,1]
	v_pk_fma_f32 v[6:7], v[116:117], v[122:123], v[114:115] op_sel_hi:[0,1,1]
	v_pk_mul_f32 v[108:109], v[108:109], v[4:5]
	v_pk_fma_f32 v[108:109], v[6:7], v[110:111], v[108:109]
	v_add_f32_e32 v9, v108, v109
	ds_write_b32 v12, v9 offset:1024
.Lscan_epi_done:
	s_or_b64 exec, exec, s[8:9]
	s_and_saveexec_b64 s[8:9], s[6:7]
	s_cbranch_execz .LBB0_828
	s_waitcnt vmcnt(6)
	v_add_u32_e32 v0, 0, v121
	s_waitcnt vmcnt(3)
	v_add_u32_e32 v12, 0x1c000, v0
	ds_read_b128 v[0:3], v12
	ds_read_b128 v[4:7], v12 offset:16
	ds_read_b128 v[8:11], v12 offset:32
	ds_read_b128 v[12:15], v12 offset:48
	v_lshlrev_b32_e32 v144, 2, v88
	s_waitcnt lgkmcnt(2)
	v_pk_add_f32 v[2:3], v[2:3], v[6:7]
	v_pk_add_f32 v[0:1], v[0:1], v[4:5]
	s_waitcnt lgkmcnt(0)
	v_pk_add_f32 v[4:5], v[10:11], v[14:15]
	v_pk_add_f32 v[6:7], v[8:9], v[12:13]
	v_pk_add_f32 v[2:3], v[2:3], v[4:5]
	v_pk_add_f32 v[0:1], v[0:1], v[6:7]
	s_nop 0
	v_pk_mov_b32 v[4:5], v[0:1], v[2:3] op_sel:[1,0]
	v_mov_b32_e32 v1, v3
	v_pk_add_f32 v[0:1], v[4:5], v[0:1]
	v_add_u32_e32 v3, 0xfdd, v89
	v_add_f32_e32 v2, v0, v1
	v_mov_b64_e32 v[0:1], s[28:29]
	v_mad_u64_u32 v[0:1], s[0:1], v3, s62, v[0:1]
	v_lshl_add_u64 v[0:1], v[0:1], 0, v[144:145]
	global_store_dword v[0:1], v2, off
.LBB0_828:
	s_or_b64 exec, exec, s[8:9]
	s_waitcnt lgkmcnt(0)
	s_barrier
	s_and_saveexec_b64 s[8:9], s[6:7]
	s_cbranch_execz .Lscan_flush_done
	v_cmp_gt_u32_e32 vcc, 3, v89
	s_and_b64 exec, exec, vcc
	s_cbranch_execz .Lscan_flush_done
	v_add_u32_e32 v12, 0x18000, v121
	ds_read_b128 v[0:3], v12
	ds_read_b128 v[4:7], v12 offset:16
	ds_read_b128 v[8:11], v12 offset:32
	ds_read_b128 v[12:15], v12 offset:48
	v_lshlrev_b32_e32 v144, 2, v88
	s_waitcnt lgkmcnt(2)
	v_pk_add_f32 v[2:3], v[2:3], v[6:7]
	v_pk_add_f32 v[0:1], v[0:1], v[4:5]
	s_waitcnt lgkmcnt(0)
	v_pk_add_f32 v[4:5], v[10:11], v[14:15]
	v_pk_add_f32 v[6:7], v[8:9], v[12:13]
	v_pk_add_f32 v[2:3], v[2:3], v[4:5]
	v_pk_add_f32 v[0:1], v[0:1], v[6:7]
	s_nop 0
	v_pk_mov_b32 v[4:5], v[0:1], v[2:3] op_sel:[1,0]
	v_mov_b32_e32 v1, v3
	v_pk_add_f32 v[0:1], v[4:5], v[0:1]
	v_add_u32_e32 v3, 0xffd, v89
	v_add_f32_e32 v2, v0, v1
	v_mov_b64_e32 v[0:1], s[28:29]
	v_mad_u64_u32 v[0:1], s[0:1], v3, s62, v[0:1]
	v_lshl_add_u64 v[0:1], v[0:1], 0, v[144:145]
	global_store_dword v[0:1], v2, off
